# split-phase SEAM4 arrival for the 44 WGs owning a 23rd G3 unit (sample tiles); G3 ids via quad-preserving permutation; G4 split-K pieces on on-time WGs gated by a counter
# speedup vs baseline: 1.0086x; 1.0007x over previous
.LBB0_962:
	s_mov_b32 s98, 0
	s_cmp_gt_i32 s88, 4
	s_cselect_b64 s[0:1], -1, 0
	s_cmp_lt_i32 s89, 5
	s_cselect_b64 s[2:3], -1, 0
	s_or_b64 s[0:1], s[0:1], s[2:3]
	s_and_b64 vcc, exec, s[0:1]
	s_cbranch_vccnz .LBB0_1037
	v_readlane_b32 s0, v249, 0
	s_cmpk_lg_i32 s96, 0x100
	s_cbranch_scc1 .Lrot_a
	s_and_b32 s99, s0, 7
	s_lshr_b32 s0, s0, 3
	s_sub_u32 s0, s0, 1
	s_and_b32 s0, s0, 31
	s_and_b32 s100, s0, 7
	s_lshl_b32 s100, s100, 2
	s_lshr_b32 s0, s0, 3
	s_or_b32 s0, s0, s100
	s_lshl_b32 s0, s0, 3
	s_or_b32 s0, s0, s99
.Lrot_a:
	s_cmpk_gt_i32 s0, 0x162b
	v_readfirstlane_b32 s10, v188
	s_cbranch_scc1 .LBB0_987
	v_readlane_b32 s1, v249, 0
	s_cmpk_lg_i32 s96, 0x100
	s_cbranch_scc1 .Lrot_b
	s_and_b32 s99, s1, 7
	s_lshr_b32 s1, s1, 3
	s_sub_u32 s1, s1, 1
	s_and_b32 s1, s1, 31
	s_and_b32 s100, s1, 7
	s_lshl_b32 s100, s100, 2
	s_lshr_b32 s1, s1, 3
	s_or_b32 s1, s1, s100
	s_lshl_b32 s1, s1, 3
	s_or_b32 s1, s1, s99
.Lrot_b:
	s_ashr_i32 s24, s1, 31
	s_lshr_b32 s0, s24, 29
	s_add_i32 s3, s1, s0
	s_and_b32 s0, s3, -8
	s_sub_i32 s4, s1, s0
	s_cmp_gt_i32 s4, 3
	s_cbranch_scc0 .LBB0_966
	s_mul_i32 s0, s4, 0x2c0
	s_mov_b32 s2, s0
	s_cbranch_execz .LBB0_967
	s_branch .LBB0_968
.LBB0_966:
.LBB0_967:
	s_mul_i32 s2, s4, 0x2c0

.LBB0_973:
	s_add_i32 s42, s42, 1
	s_mul_i32 s0, s42, s45
	s_mul_hi_u32 s1, s42, s46
	s_add_i32 s1, s1, s0
	s_mul_i32 s0, s42, s46
	v_readlane_b32 s13, v249, 0
	s_cmpk_lg_i32 s96, 0x100
	s_cbranch_scc1 .Lrot_c
	s_and_b32 s99, s13, 7
	s_lshr_b32 s13, s13, 3
	s_sub_u32 s13, s13, 1
	s_and_b32 s13, s13, 31
	s_and_b32 s100, s13, 7
	s_lshl_b32 s100, s100, 2
	s_lshr_b32 s13, s13, 3
	s_or_b32 s13, s13, s100
	s_lshl_b32 s13, s13, 3
	s_or_b32 s13, s13, s99
.Lrot_c:
	s_cmp_lg_u32 s42, 21
	s_cbranch_scc1 .Lg3w_skip
	s_cmpk_lg_i32 s96, 0x100
	s_cbranch_scc1 .Lg3w_skip
	s_cmp_gt_u32 s13, 43
	s_cbranch_scc1 .Lg3w_skip
	v_mov_b32_e32 v4, 0x310080
.Lg3w_spin:
	global_load_dword v5, v4, s[30:31] sc1
	s_waitcnt vmcnt(0)
	v_readfirstlane_b32 s99, v5
	s_cmp_ge_u32 s99, 8
	s_cbranch_scc1 .Lg3w_ok
	s_sleep 1
	s_branch .Lg3w_spin

.Lg3w_skip:
	s_add_u32 s16, s0, s13
	s_addc_u32 s17, s1, s24
	v_cmp_gt_i64_e32 vcc, s[16:17], v[142:143]
	v_cmp_lt_i64_e64 s[0:1], s[16:17], v[140:141]
	s_cbranch_vccnz .LBB0_979
	s_ashr_i32 s12, s16, 31
	s_lshr_b32 s12, s12, 29
	s_add_i32 s14, s16, s12
	s_and_b32 s12, s14, -8
	s_sub_i32 s15, s16, s12
	s_cmp_gt_i32 s15, 3
	s_mov_b64 s[12:13], -1
	s_cbranch_scc0 .LBB0_976
	s_mul_i32 s12, s15, 0x2c0
	s_mov_b32 s16, s12
	s_mov_b64 s[12:13], 0
.LBB0_976:
	s_andn2_b64 vcc, exec, s[12:13]
	s_cbranch_vccnz .LBB0_978
	s_mul_i32 s16, s15, 0x2c0
.LBB0_978:
	s_ashr_i32 s12, s14, 3
	s_add_i32 s12, s16, s12
	s_cmpk_ge_i32 s14, 0x1600
	s_cselect_b32 s12, s14, s12
	s_mul_hi_i32 s13, s12, 0x2e8ba2e9
	s_lshr_b32 s14, s13, 31
	s_ashr_i32 s13, s13, 5
	s_add_i32 s13, s13, s14
	s_lshl_b32 s14, s13, 3
	s_sub_i32 s15, 0x102, s14
	s_min_i32 s15, s15, 8
	s_abs_i32 s16, s15
	v_cvt_f32_u32_e32 v0, s16
	s_sub_i32 s18, 0, s16
	s_mulk_i32 s13, 0xb0
	s_sub_i32 s13, s12, s13
	v_rcp_iflag_f32_e32 v0, v0
	s_abs_i32 s12, s13
	s_xor_b32 s17, s13, s15
	s_ashr_i32 s17, s17, 31
	v_mul_f32_e32 v0, 0x4f7ffffe, v0
	v_cvt_u32_f32_e32 v0, v0
	s_nop 0
	v_readfirstlane_b32 s19, v0
	s_mul_i32 s18, s18, s19
	s_mul_hi_u32 s18, s19, s18
	s_add_i32 s19, s19, s18
	s_mul_hi_u32 s18, s12, s19
	s_mul_i32 s19, s18, s16
	s_sub_i32 s12, s12, s19
	s_add_i32 s36, s18, 1
	s_sub_i32 s19, s12, s16
	s_cmp_ge_u32 s12, s16
	s_cselect_b32 s18, s36, s18
	s_cselect_b32 s12, s19, s12
	s_add_i32 s19, s18, 1
	s_cmp_ge_u32 s12, s16
	s_cselect_b32 s12, s19, s18
	s_xor_b32 s12, s12, s17
	s_sub_i32 s12, s12, s17
	s_mul_i32 s15, s12, s15
	s_sub_i32 s13, s13, s15
	s_add_i32 s14, s14, s13

.LBB0_983:
	v_lshl_add_u32 v144, s20, 8, v148
	v_ashrrev_i32_e32 v145, 31, v144
	v_lshl_add_u64 v[146:147], v[144:145], 2, s[6:7]
	v_pk_mul_f32 v[124:125], v[116:117], v[124:125]
	v_pk_mul_f32 v[158:159], v[114:115], v[122:123]
	v_pk_mul_f32 v[160:161], v[112:113], v[120:121]
	v_pk_mul_f32 v[126:127], v[118:119], v[126:127]
	v_lshl_or_b32 v156, s50, 7, v150
	v_mov_b64_e32 v[120:121], s[4:5]
	v_ashrrev_i32_e32 v157, 31, v156
	v_mad_i64_i32 v[162:163], s[22:23], v144, s49, v[120:121]
	v_or_b32_e32 v164, 16, v144
	v_lshlrev_b64 v[122:123], 1, v[156:157]
	v_ashrrev_i32_e32 v165, 31, v164
	v_lshl_add_u64 v[156:157], v[162:163], 0, v[122:123]
	v_lshl_add_u64 v[162:163], v[164:165], 2, s[6:7]
	v_pk_mul_f32 v[102:103], v[98:99], v[102:103]
	v_pk_mul_f32 v[100:101], v[96:97], v[100:101]
	v_pk_mul_f32 v[110:111], v[106:107], v[110:111]
	v_pk_mul_f32 v[108:109], v[104:105], v[108:109]
	v_pk_mul_f32 v[86:87], v[82:83], v[86:87]
	v_pk_mul_f32 v[84:85], v[80:81], v[84:85]
	v_pk_mul_f32 v[94:95], v[90:91], v[94:95]
	v_pk_mul_f32 v[92:93], v[88:89], v[92:93]
	v_pk_mul_f32 v[66:67], v[70:71], v[66:67]
	v_pk_mul_f32 v[64:65], v[68:69], v[64:65]
	v_pk_mul_f32 v[78:79], v[74:75], v[78:79]
	v_pk_mul_f32 v[76:77], v[72:73], v[76:77]
	v_pk_mul_f32 v[54:55], v[50:51], v[54:55]
	v_pk_mul_f32 v[52:53], v[48:49], v[52:53]
	v_pk_mul_f32 v[62:63], v[58:59], v[62:63]
	v_pk_mul_f32 v[60:61], v[56:57], v[60:61]
	v_pk_mul_f32 v[38:39], v[34:35], v[38:39]
	v_pk_mul_f32 v[36:37], v[32:33], v[36:37]
	v_pk_mul_f32 v[46:47], v[42:43], v[46:47]
	v_pk_mul_f32 v[44:45], v[40:41], v[44:45]
	v_pk_mul_f32 v[22:23], v[18:19], v[22:23]
	v_pk_mul_f32 v[20:21], v[16:17], v[20:21]
	v_pk_mul_f32 v[30:31], v[26:27], v[30:31]
	v_pk_mul_f32 v[28:29], v[24:25], v[28:29]
	v_pk_mul_f32 v[6:7], v[2:3], v[6:7]
	v_pk_mul_f32 v[4:5], v[0:1], v[4:5]
	v_pk_mul_f32 v[14:15], v[10:11], v[14:15]
	v_pk_mul_f32 v[12:13], v[8:9], v[12:13]
	s_andn2_b64 vcc, exec, s[0:1]
	s_mov_b64 s[0:1], -1
	s_waitcnt vmcnt(7)
	v_fmamk_f32 v145, v228, 0x3a800000, v154
	v_rsq_f32_e32 v145, v145
	s_nop 0
	v_mul_f32_e32 v166, 0xbfb8aa3b, v145
	v_pk_mul_f32 v[116:117], v[116:117], v[166:167] op_sel_hi:[1,0]
	v_pk_mul_f32 v[114:115], v[114:115], v[166:167] op_sel_hi:[1,0]
	v_pk_mul_f32 v[112:113], v[112:113], v[166:167] op_sel_hi:[1,0]
	v_pk_mul_f32 v[118:119], v[118:119], v[166:167] op_sel_hi:[1,0]
	v_exp_f32_e32 v116, v116
	v_exp_f32_e32 v117, v117
	v_exp_f32_e32 v112, v112
	v_exp_f32_e32 v114, v114
	v_exp_f32_e32 v115, v115
	v_exp_f32_e32 v113, v113
	v_exp_f32_e32 v118, v118
	v_exp_f32_e32 v119, v119
	v_pk_add_f32 v[116:117], v[116:117], 1.0 op_sel_hi:[1,0]
	v_pk_add_f32 v[114:115], v[114:115], 1.0 op_sel_hi:[1,0]
	v_pk_add_f32 v[112:113], v[112:113], 1.0 op_sel_hi:[1,0]
	v_pk_add_f32 v[118:119], v[118:119], 1.0 op_sel_hi:[1,0]
	v_rcp_f32_e32 v116, v116
	v_rcp_f32_e32 v117, v117
	v_rcp_f32_e32 v112, v112
	v_rcp_f32_e32 v114, v114
	v_rcp_f32_e32 v115, v115
	v_rcp_f32_e32 v113, v113
	v_rcp_f32_e32 v118, v118
	v_rcp_f32_e32 v119, v119
	v_mul_f32_e32 v168, v145, v145
	v_pk_mul_f32 v[124:125], v[124:125], v[168:169] op_sel_hi:[1,0]
	v_pk_mul_f32 v[160:161], v[160:161], v[168:169] op_sel_hi:[1,0]
	v_pk_mul_f32 v[158:159], v[158:159], v[168:169] op_sel_hi:[1,0]
	v_pk_mul_f32 v[126:127], v[126:127], v[168:169] op_sel_hi:[1,0]
	v_pk_mul_f32 v[116:117], v[124:125], v[116:117]
	v_pk_mul_f32 v[124:125], v[158:159], v[114:115]
	v_pk_mul_f32 v[114:115], v[160:161], v[112:113]
	v_pk_mul_f32 v[118:119], v[126:127], v[118:119]
	v_cvt_pk_bf16_f32 v112, v116, v117
	s_nop 0
	v_cvt_pk_bf16_f32 v113, v118, v119
	v_cvt_pk_bf16_f32 v114, v114, v115
	v_cvt_pk_bf16_f32 v115, v124, v125
	global_store_dwordx4 v[156:157], v[112:115], off
	s_nop 0
	s_nop 0
	v_or_b32_e32 v112, 32, v144
	v_mad_i64_i32 v[114:115], s[22:23], v164, s49, v[120:121]
	v_lshl_add_u64 v[114:115], v[114:115], 0, v[122:123]
	s_waitcnt vmcnt(7)
	v_fmamk_f32 v113, v229, 0x3a800000, v154
	v_rsq_f32_e32 v119, v113
	v_ashrrev_i32_e32 v113, 31, v112
	v_lshl_add_u64 v[116:117], v[112:113], 2, s[6:7]
	v_mul_f32_e32 v118, 0xbfb8aa3b, v119
	v_pk_mul_f32 v[98:99], v[98:99], v[118:119] op_sel_hi:[1,0]
	v_pk_mul_f32 v[96:97], v[96:97], v[118:119] op_sel_hi:[1,0]
	v_pk_mul_f32 v[106:107], v[106:107], v[118:119] op_sel_hi:[1,0]
	v_pk_mul_f32 v[104:105], v[104:105], v[118:119] op_sel_hi:[1,0]
	v_exp_f32_e32 v96, v96
	v_exp_f32_e32 v98, v98
	v_exp_f32_e32 v99, v99
	v_exp_f32_e32 v97, v97
	v_exp_f32_e32 v104, v104
	v_exp_f32_e32 v105, v105
	v_exp_f32_e32 v106, v106
	v_exp_f32_e32 v107, v107
	v_pk_add_f32 v[98:99], v[98:99], 1.0 op_sel_hi:[1,0]
	v_pk_add_f32 v[96:97], v[96:97], 1.0 op_sel_hi:[1,0]
	v_pk_add_f32 v[104:105], v[104:105], 1.0 op_sel_hi:[1,0]
	v_pk_add_f32 v[106:107], v[106:107], 1.0 op_sel_hi:[1,0]
	v_rcp_f32_e32 v96, v96
	v_rcp_f32_e32 v98, v98
	v_rcp_f32_e32 v99, v99
	v_rcp_f32_e32 v97, v97
	v_rcp_f32_e32 v104, v104
	v_rcp_f32_e32 v105, v105
	v_rcp_f32_e32 v106, v106
	v_rcp_f32_e32 v107, v107
	v_mul_f32_e32 v124, v119, v119
	v_pk_mul_f32 v[100:101], v[100:101], v[124:125] op_sel_hi:[1,0]
	v_pk_mul_f32 v[102:103], v[102:103], v[124:125] op_sel_hi:[1,0]
	v_pk_mul_f32 v[108:109], v[108:109], v[124:125] op_sel_hi:[1,0]
	v_pk_mul_f32 v[110:111], v[110:111], v[124:125] op_sel_hi:[1,0]
	v_pk_mul_f32 v[102:103], v[102:103], v[98:99]
	v_pk_mul_f32 v[98:99], v[100:101], v[96:97]
	v_pk_mul_f32 v[106:107], v[110:111], v[106:107]
	v_pk_mul_f32 v[104:105], v[108:109], v[104:105]
	s_nop 0
	v_cvt_pk_bf16_f32 v96, v104, v105
	v_cvt_pk_bf16_f32 v97, v106, v107
	v_cvt_pk_bf16_f32 v98, v98, v99
	v_cvt_pk_bf16_f32 v99, v102, v103
	global_store_dwordx4 v[114:115], v[96:99], off
	s_nop 0
	s_nop 0
	v_or_b32_e32 v96, 48, v144
	v_mad_i64_i32 v[98:99], s[22:23], v112, s49, v[120:121]
	v_lshl_add_u64 v[98:99], v[98:99], 0, v[122:123]
	s_waitcnt vmcnt(7)
	v_fmamk_f32 v97, v230, 0x3a800000, v154
	v_rsq_f32_e32 v103, v97
	v_ashrrev_i32_e32 v97, 31, v96
	v_lshl_add_u64 v[100:101], v[96:97], 2, s[6:7]
	v_mul_f32_e32 v102, 0xbfb8aa3b, v103
	v_pk_mul_f32 v[82:83], v[82:83], v[102:103] op_sel_hi:[1,0]
	v_pk_mul_f32 v[80:81], v[80:81], v[102:103] op_sel_hi:[1,0]
	v_pk_mul_f32 v[90:91], v[90:91], v[102:103] op_sel_hi:[1,0]
	v_pk_mul_f32 v[88:89], v[88:89], v[102:103] op_sel_hi:[1,0]
	v_exp_f32_e32 v80, v80
	v_exp_f32_e32 v82, v82
	v_exp_f32_e32 v83, v83
	v_exp_f32_e32 v81, v81
	v_exp_f32_e32 v88, v88
	v_exp_f32_e32 v89, v89
	v_exp_f32_e32 v90, v90
	v_exp_f32_e32 v91, v91
	v_pk_add_f32 v[82:83], v[82:83], 1.0 op_sel_hi:[1,0]
	v_pk_add_f32 v[80:81], v[80:81], 1.0 op_sel_hi:[1,0]
	v_pk_add_f32 v[88:89], v[88:89], 1.0 op_sel_hi:[1,0]
	v_pk_add_f32 v[90:91], v[90:91], 1.0 op_sel_hi:[1,0]
	v_rcp_f32_e32 v80, v80
	v_rcp_f32_e32 v82, v82
	v_rcp_f32_e32 v83, v83
	v_rcp_f32_e32 v81, v81
	v_rcp_f32_e32 v88, v88
	v_rcp_f32_e32 v89, v89
	v_rcp_f32_e32 v90, v90
	v_rcp_f32_e32 v91, v91
	v_mul_f32_e32 v104, v103, v103
	v_pk_mul_f32 v[84:85], v[84:85], v[104:105] op_sel_hi:[1,0]
	v_pk_mul_f32 v[86:87], v[86:87], v[104:105] op_sel_hi:[1,0]
	v_pk_mul_f32 v[92:93], v[92:93], v[104:105] op_sel_hi:[1,0]
	v_pk_mul_f32 v[94:95], v[94:95], v[104:105] op_sel_hi:[1,0]
	v_pk_mul_f32 v[86:87], v[86:87], v[82:83]
	v_pk_mul_f32 v[82:83], v[84:85], v[80:81]
	v_pk_mul_f32 v[90:91], v[94:95], v[90:91]
	v_pk_mul_f32 v[88:89], v[92:93], v[88:89]
	s_nop 0
	v_cvt_pk_bf16_f32 v80, v88, v89
	v_cvt_pk_bf16_f32 v81, v90, v91
	v_cvt_pk_bf16_f32 v82, v82, v83
	v_cvt_pk_bf16_f32 v83, v86, v87
	global_store_dwordx4 v[98:99], v[80:83], off
	s_nop 0
	s_waitcnt vmcnt(7)
	v_fmamk_f32 v80, v231, 0x3a800000, v154
	v_rsq_f32_e32 v83, v80
	v_mad_i64_i32 v[80:81], s[22:23], v96, s49, v[120:121]
	v_lshl_add_u64 v[80:81], v[80:81], 0, v[122:123]
	v_mul_f32_e32 v82, 0xbfb8aa3b, v83
	v_pk_mul_f32 v[70:71], v[70:71], v[82:83] op_sel_hi:[1,0]
	v_pk_mul_f32 v[68:69], v[68:69], v[82:83] op_sel_hi:[1,0]
	v_pk_mul_f32 v[74:75], v[74:75], v[82:83] op_sel_hi:[1,0]
	v_pk_mul_f32 v[72:73], v[72:73], v[82:83] op_sel_hi:[1,0]
	v_exp_f32_e32 v68, v68
	v_exp_f32_e32 v70, v70
	v_exp_f32_e32 v71, v71
	v_exp_f32_e32 v69, v69
	v_exp_f32_e32 v72, v72
	v_exp_f32_e32 v73, v73
	v_exp_f32_e32 v74, v74
	v_exp_f32_e32 v75, v75
	v_pk_add_f32 v[70:71], v[70:71], 1.0 op_sel_hi:[1,0]
	v_pk_add_f32 v[68:69], v[68:69], 1.0 op_sel_hi:[1,0]
	v_pk_add_f32 v[72:73], v[72:73], 1.0 op_sel_hi:[1,0]
	v_pk_add_f32 v[74:75], v[74:75], 1.0 op_sel_hi:[1,0]
	v_rcp_f32_e32 v68, v68
	v_rcp_f32_e32 v70, v70
	v_rcp_f32_e32 v71, v71
	v_rcp_f32_e32 v69, v69
	v_rcp_f32_e32 v72, v72
	v_rcp_f32_e32 v73, v73
	v_rcp_f32_e32 v74, v74
	v_rcp_f32_e32 v75, v75
	v_mul_f32_e32 v84, v83, v83
	v_pk_mul_f32 v[64:65], v[64:65], v[84:85] op_sel_hi:[1,0]
	v_pk_mul_f32 v[66:67], v[66:67], v[84:85] op_sel_hi:[1,0]
	v_pk_mul_f32 v[76:77], v[76:77], v[84:85] op_sel_hi:[1,0]
	v_pk_mul_f32 v[78:79], v[78:79], v[84:85] op_sel_hi:[1,0]
	v_pk_mul_f32 v[70:71], v[66:67], v[70:71]
	v_pk_mul_f32 v[66:67], v[64:65], v[68:69]
	v_pk_mul_f32 v[74:75], v[78:79], v[74:75]
	v_pk_mul_f32 v[72:73], v[76:77], v[72:73]
	s_nop 0
	v_cvt_pk_bf16_f32 v64, v72, v73
	v_cvt_pk_bf16_f32 v65, v74, v75
	v_cvt_pk_bf16_f32 v66, v66, v67
	v_cvt_pk_bf16_f32 v67, v70, v71
	global_store_dwordx4 v[80:81], v[64:67], off
	s_nop 0
	s_nop 0
	v_add_u32_e32 v65, 0x80, v144
	s_waitcnt vmcnt(7)
	v_fmamk_f32 v64, v232, 0x3a800000, v154
	v_rsq_f32_e32 v67, v64
	v_mad_i64_i32 v[64:65], s[22:23], v65, s49, v[120:121]
	v_lshl_add_u64 v[64:65], v[64:65], 0, v[122:123]
	v_mul_f32_e32 v66, 0xbfb8aa3b, v67
	v_pk_mul_f32 v[50:51], v[50:51], v[66:67] op_sel_hi:[1,0]
	v_pk_mul_f32 v[48:49], v[48:49], v[66:67] op_sel_hi:[1,0]
	v_pk_mul_f32 v[58:59], v[58:59], v[66:67] op_sel_hi:[1,0]
	v_pk_mul_f32 v[56:57], v[56:57], v[66:67] op_sel_hi:[1,0]
	v_exp_f32_e32 v48, v48
	v_exp_f32_e32 v50, v50
	v_exp_f32_e32 v51, v51
	v_exp_f32_e32 v49, v49
	v_exp_f32_e32 v56, v56
	v_exp_f32_e32 v57, v57
	v_exp_f32_e32 v58, v58
	v_exp_f32_e32 v59, v59
	v_pk_add_f32 v[50:51], v[50:51], 1.0 op_sel_hi:[1,0]
	v_pk_add_f32 v[48:49], v[48:49], 1.0 op_sel_hi:[1,0]
	v_pk_add_f32 v[56:57], v[56:57], 1.0 op_sel_hi:[1,0]
	v_pk_add_f32 v[58:59], v[58:59], 1.0 op_sel_hi:[1,0]
	v_rcp_f32_e32 v48, v48
	v_rcp_f32_e32 v50, v50
	v_rcp_f32_e32 v51, v51
	v_rcp_f32_e32 v49, v49
	v_rcp_f32_e32 v56, v56
	v_rcp_f32_e32 v57, v57
	v_rcp_f32_e32 v58, v58
	v_rcp_f32_e32 v59, v59
	v_mul_f32_e32 v68, v67, v67
	v_pk_mul_f32 v[52:53], v[52:53], v[68:69] op_sel_hi:[1,0]
	v_pk_mul_f32 v[54:55], v[54:55], v[68:69] op_sel_hi:[1,0]
	v_pk_mul_f32 v[60:61], v[60:61], v[68:69] op_sel_hi:[1,0]
	v_pk_mul_f32 v[62:63], v[62:63], v[68:69] op_sel_hi:[1,0]
	v_pk_mul_f32 v[54:55], v[54:55], v[50:51]
	v_pk_mul_f32 v[50:51], v[52:53], v[48:49]
	v_pk_mul_f32 v[58:59], v[62:63], v[58:59]
	v_pk_mul_f32 v[56:57], v[60:61], v[56:57]
	s_nop 0
	v_cvt_pk_bf16_f32 v48, v56, v57
	v_cvt_pk_bf16_f32 v49, v58, v59
	v_cvt_pk_bf16_f32 v50, v50, v51
	v_cvt_pk_bf16_f32 v51, v54, v55
	global_store_dwordx4 v[64:65], v[48:51], off
	s_nop 0
	s_nop 0
	v_add_u32_e32 v49, 0x90, v144
	s_waitcnt vmcnt(7)
	v_fmamk_f32 v48, v233, 0x3a800000, v154
	v_rsq_f32_e32 v51, v48
	v_mad_i64_i32 v[48:49], s[22:23], v49, s49, v[120:121]
	v_lshl_add_u64 v[48:49], v[48:49], 0, v[122:123]
	v_mul_f32_e32 v50, 0xbfb8aa3b, v51
	v_pk_mul_f32 v[34:35], v[34:35], v[50:51] op_sel_hi:[1,0]
	v_pk_mul_f32 v[32:33], v[32:33], v[50:51] op_sel_hi:[1,0]
	v_pk_mul_f32 v[42:43], v[42:43], v[50:51] op_sel_hi:[1,0]
	v_pk_mul_f32 v[40:41], v[40:41], v[50:51] op_sel_hi:[1,0]
	v_exp_f32_e32 v32, v32
	v_exp_f32_e32 v34, v34
	v_exp_f32_e32 v35, v35
	v_exp_f32_e32 v33, v33
	v_exp_f32_e32 v40, v40
	v_exp_f32_e32 v41, v41
	v_exp_f32_e32 v42, v42
	v_exp_f32_e32 v43, v43
	v_pk_add_f32 v[34:35], v[34:35], 1.0 op_sel_hi:[1,0]
	v_pk_add_f32 v[32:33], v[32:33], 1.0 op_sel_hi:[1,0]
	v_pk_add_f32 v[40:41], v[40:41], 1.0 op_sel_hi:[1,0]
	v_pk_add_f32 v[42:43], v[42:43], 1.0 op_sel_hi:[1,0]
	v_rcp_f32_e32 v32, v32
	v_rcp_f32_e32 v34, v34
	v_rcp_f32_e32 v35, v35
	v_rcp_f32_e32 v33, v33
	v_rcp_f32_e32 v40, v40
	v_rcp_f32_e32 v41, v41
	v_rcp_f32_e32 v42, v42
	v_rcp_f32_e32 v43, v43
	v_mul_f32_e32 v52, v51, v51
	v_pk_mul_f32 v[36:37], v[36:37], v[52:53] op_sel_hi:[1,0]
	v_pk_mul_f32 v[38:39], v[38:39], v[52:53] op_sel_hi:[1,0]
	v_pk_mul_f32 v[44:45], v[44:45], v[52:53] op_sel_hi:[1,0]
	v_pk_mul_f32 v[46:47], v[46:47], v[52:53] op_sel_hi:[1,0]
	v_pk_mul_f32 v[38:39], v[38:39], v[34:35]
	v_pk_mul_f32 v[34:35], v[36:37], v[32:33]
	v_pk_mul_f32 v[42:43], v[46:47], v[42:43]
	v_pk_mul_f32 v[40:41], v[44:45], v[40:41]
	s_nop 0
	v_cvt_pk_bf16_f32 v32, v40, v41
	v_cvt_pk_bf16_f32 v33, v42, v43
	v_cvt_pk_bf16_f32 v34, v34, v35
	v_cvt_pk_bf16_f32 v35, v38, v39
	global_store_dwordx4 v[48:49], v[32:35], off
	s_nop 0
	s_nop 0
	v_add_u32_e32 v33, 0xa0, v144
	s_waitcnt vmcnt(7)
	v_fmamk_f32 v32, v234, 0x3a800000, v154
	v_rsq_f32_e32 v35, v32
	v_mad_i64_i32 v[32:33], s[22:23], v33, s49, v[120:121]
	v_lshl_add_u64 v[32:33], v[32:33], 0, v[122:123]
	v_mul_f32_e32 v34, 0xbfb8aa3b, v35
	v_pk_mul_f32 v[18:19], v[18:19], v[34:35] op_sel_hi:[1,0]
	v_pk_mul_f32 v[16:17], v[16:17], v[34:35] op_sel_hi:[1,0]
	v_pk_mul_f32 v[26:27], v[26:27], v[34:35] op_sel_hi:[1,0]
	v_pk_mul_f32 v[24:25], v[24:25], v[34:35] op_sel_hi:[1,0]
	v_exp_f32_e32 v16, v16
	v_exp_f32_e32 v18, v18
	v_exp_f32_e32 v19, v19
	v_exp_f32_e32 v17, v17
	v_exp_f32_e32 v24, v24
	v_exp_f32_e32 v25, v25
	v_exp_f32_e32 v26, v26
	v_exp_f32_e32 v27, v27
	v_pk_add_f32 v[18:19], v[18:19], 1.0 op_sel_hi:[1,0]
	v_pk_add_f32 v[16:17], v[16:17], 1.0 op_sel_hi:[1,0]
	v_pk_add_f32 v[24:25], v[24:25], 1.0 op_sel_hi:[1,0]
	v_pk_add_f32 v[26:27], v[26:27], 1.0 op_sel_hi:[1,0]
	v_rcp_f32_e32 v16, v16
	v_rcp_f32_e32 v18, v18
	v_rcp_f32_e32 v19, v19
	v_rcp_f32_e32 v17, v17
	v_rcp_f32_e32 v24, v24
	v_rcp_f32_e32 v25, v25
	v_rcp_f32_e32 v26, v26
	v_rcp_f32_e32 v27, v27
	v_mul_f32_e32 v36, v35, v35
	v_pk_mul_f32 v[20:21], v[20:21], v[36:37] op_sel_hi:[1,0]
	v_pk_mul_f32 v[22:23], v[22:23], v[36:37] op_sel_hi:[1,0]
	v_pk_mul_f32 v[28:29], v[28:29], v[36:37] op_sel_hi:[1,0]
	v_pk_mul_f32 v[30:31], v[30:31], v[36:37] op_sel_hi:[1,0]
	v_pk_mul_f32 v[22:23], v[22:23], v[18:19]
	v_pk_mul_f32 v[18:19], v[20:21], v[16:17]
	v_pk_mul_f32 v[26:27], v[30:31], v[26:27]
	v_pk_mul_f32 v[24:25], v[28:29], v[24:25]
	s_nop 0
	v_cvt_pk_bf16_f32 v16, v24, v25
	v_cvt_pk_bf16_f32 v17, v26, v27
	v_cvt_pk_bf16_f32 v18, v18, v19
	v_cvt_pk_bf16_f32 v19, v22, v23
	global_store_dwordx4 v[32:33], v[16:19], off
	s_nop 0
	s_nop 0
	v_add_u32_e32 v17, 0xb0, v144
	s_waitcnt vmcnt(7)
	v_fmamk_f32 v16, v235, 0x3a800000, v154
	v_rsq_f32_e32 v19, v16
	v_mad_i64_i32 v[16:17], s[22:23], v17, s49, v[120:121]
	v_lshl_add_u64 v[16:17], v[16:17], 0, v[122:123]
	v_mul_f32_e32 v18, 0xbfb8aa3b, v19
	v_pk_mul_f32 v[2:3], v[2:3], v[18:19] op_sel_hi:[1,0]
	v_pk_mul_f32 v[0:1], v[0:1], v[18:19] op_sel_hi:[1,0]
	v_pk_mul_f32 v[10:11], v[10:11], v[18:19] op_sel_hi:[1,0]
	v_pk_mul_f32 v[8:9], v[8:9], v[18:19] op_sel_hi:[1,0]
	v_exp_f32_e32 v0, v0
	v_exp_f32_e32 v2, v2
	v_exp_f32_e32 v3, v3
	v_exp_f32_e32 v1, v1
	v_exp_f32_e32 v8, v8
	v_exp_f32_e32 v9, v9
	v_exp_f32_e32 v10, v10
	v_exp_f32_e32 v11, v11
	v_pk_add_f32 v[2:3], v[2:3], 1.0 op_sel_hi:[1,0]
	v_pk_add_f32 v[0:1], v[0:1], 1.0 op_sel_hi:[1,0]
	v_pk_add_f32 v[8:9], v[8:9], 1.0 op_sel_hi:[1,0]
	v_pk_add_f32 v[10:11], v[10:11], 1.0 op_sel_hi:[1,0]
	v_rcp_f32_e32 v0, v0
	v_rcp_f32_e32 v2, v2
	v_rcp_f32_e32 v3, v3
	v_rcp_f32_e32 v1, v1
	v_rcp_f32_e32 v8, v8
	v_rcp_f32_e32 v9, v9
	v_rcp_f32_e32 v10, v10
	v_rcp_f32_e32 v11, v11
	v_mul_f32_e32 v20, v19, v19
	v_pk_mul_f32 v[4:5], v[4:5], v[20:21] op_sel_hi:[1,0]
	v_pk_mul_f32 v[6:7], v[6:7], v[20:21] op_sel_hi:[1,0]
	v_pk_mul_f32 v[12:13], v[12:13], v[20:21] op_sel_hi:[1,0]
	v_pk_mul_f32 v[14:15], v[14:15], v[20:21] op_sel_hi:[1,0]
	v_pk_mul_f32 v[6:7], v[6:7], v[2:3]
	v_pk_mul_f32 v[2:3], v[4:5], v[0:1]
	v_pk_mul_f32 v[10:11], v[14:15], v[10:11]
	v_pk_mul_f32 v[8:9], v[12:13], v[8:9]
	s_nop 0
	v_cvt_pk_bf16_f32 v0, v8, v9
	v_cvt_pk_bf16_f32 v1, v10, v11
	v_cvt_pk_bf16_f32 v2, v2, v3
	v_cvt_pk_bf16_f32 v3, v6, v7
	global_store_dwordx4 v[16:17], v[0:3], off
	s_cbranch_vccnz .LBB0_972
	s_cmp_lg_u32 s42, 22
	s_cbranch_scc1 .Lea3_skip
	s_cmpk_lg_i32 s96, 0x100
	s_cbranch_scc1 .Lea3_skip
	s_waitcnt vmcnt(0) lgkmcnt(0)
	s_barrier
	s_mov_b32 s98, 1
	v_cmp_eq_u32_e32 vcc, 0, v188
	s_and_saveexec_b64 s[34:35], vcc
	s_cbranch_execz .Lea3_done
	v_mov_b32_e32 v2, 0x23fe0
	ds_read_b32 v3, v2
	ds_read_b32 v4, v2 offset:4
	v_readlane_b32 s36, v249, 20
	v_readlane_b32 s50, v249, 18
	v_readlane_b32 s51, v249, 19
	s_lshl_b32 s36, s36, 8
	s_add_u32 s36, s50, s36
	s_addc_u32 s37, s51, 0
	v_mov_b32_e32 v5, 0x1000
	v_mov_b32_e32 v6, 1
	s_nop 1
	global_atomic_add v6, v5, v6, s[36:37] offset:1024 sc0
	s_waitcnt vmcnt(0) lgkmcnt(0)
	v_add_u32_e32 v6, 1, v6
	v_lshl_add_u32 v7, v3, 2, v3
	v_cmp_eq_u32_e32 vcc, v6, v7
	s_and_saveexec_b64 s[52:53], vcc
	s_cbranch_execz .Lea3_done
	buffer_wbl2 sc1
	s_waitcnt vmcnt(0)
	v_mov_b32_e32 v5, 0x313000
	v_mov_b32_e32 v6, 1
	global_atomic_add v6, v5, v6, s[30:31] offset:1024 sc0
	s_waitcnt vmcnt(0)
	v_add_u32_e32 v6, 1, v6
	v_lshl_add_u32 v7, v4, 2, v4
	v_cmp_eq_u32_e32 vcc, v6, v7
	s_and_saveexec_b64 s[54:55], vcc
	s_cbranch_execz .Lea3_done
	v_mov_b32_e32 v5, 0x313500
	v_mov_b32_e32 v6, 1
	global_atomic_add v5, v6, s[30:31]
	s_waitcnt vmcnt(0)

.Lea3_skip:
	s_andn2_b64 vcc, exec, s[2:3]
	s_cbranch_vccnz .LBB0_971
	s_barrier
	s_branch .LBB0_971

.LBB0_987:
	s_cmp_lt_i32 s89, 6
	s_cbranch_scc1 .LBB0_1037
	s_waitcnt vmcnt(0)
	v_cmp_eq_u32_e32 vcc, 0, v188
	s_waitcnt vmcnt(0) lgkmcnt(0)
	s_barrier
	s_and_saveexec_b64 s[0:1], vcc
	s_cbranch_execz .LBB0_1036
	s_cmp_lg_u32 s98, 1
	s_cbranch_scc1 .Lea3_normal
	buffer_wbl2 sc1
	s_waitcnt vmcnt(0) lgkmcnt(0)
	v_mov_b32_e32 v0, 0x3100c0
	v_mov_b32_e32 v1, 1
	global_atomic_add v0, v1, s[30:31]
	v_mov_b32_e32 v0, 0x313500
.Lea3_wait:
	global_load_dword v1, v0, s[30:31] sc1
	s_waitcnt vmcnt(0)
	v_cmp_ne_u32_e32 vcc, 4, v1
	s_cbranch_vccnz .Lea3_waited
	s_sleep 1
	s_branch .Lea3_wait

.LBB0_1037:
	s_mov_b32 s98, 0
	s_cmp_lt_i32 s88, 6
	s_cselect_b64 s[6:7], -1, 0
	s_cmp_gt_i32 s88, 5
	s_cselect_b64 s[0:1], -1, 0
	s_cmp_lt_i32 s89, 6
	s_cselect_b64 s[2:3], -1, 0
	s_or_b64 s[0:1], s[0:1], s[2:3]
	s_and_b64 vcc, exec, s[0:1]
	s_cbranch_vccnz .LBB0_1109
	v_readlane_b32 s2, v249, 0
	s_cmpk_lt_i32 s2, 0x400
	s_cselect_b64 s[0:1], -1, 0
	s_cmpk_gt_i32 s2, 0x3ff
	v_readfirstlane_b32 s4, v188
	s_cbranch_scc1 .LBB0_1044
	v_readlane_b32 s3, v249, 0
	s_ashr_i32 s2, s3, 31
	s_lshr_b32 s2, s2, 29
	s_add_i32 s9, s3, s2
	s_and_b32 s2, s9, -8
	s_sub_i32 s5, s3, s2
	s_cmp_gt_i32 s5, -1
	s_cbranch_scc0 .LBB0_1041
	s_lshl_b32 s8, s5, 7
	s_ashr_i32 s2, s9, 3
	s_cbranch_execz .LBB0_1042
	s_branch .LBB0_1043

.LBB0_1102:
	v_readlane_b32 s0, v249, 0
	s_cmpk_lg_i32 s96, 0x100
	s_cbranch_scc1 .Lpc_cmp
	s_movk_i32 s99, 0x1000
	s_sub_u32 s100, s0, 24
	s_cmp_lt_u32 s100, 40
	s_cselect_b32 s99, s100, s99
	s_sub_u32 s100, s0, 88
	s_cmp_lt_u32 s100, 40
	s_cbranch_scc0 .Lpc_1
	s_add_u32 s99, s100, 40
.Lpc_1:
	s_sub_u32 s100, s0, 152
	s_cmp_lt_u32 s100, 8
	s_cbranch_scc0 .Lpc_2
	s_add_u32 s99, s100, 80
.Lpc_2:
	s_mov_b32 s0, s99
.Lpc_cmp:
	s_cmpk_gt_i32 s0, 0x57
	s_cbranch_scc1 .LBB0_1109
	s_cmpk_lg_i32 s96, 0x100
	s_cbranch_scc1 .Lpcw_skip
	v_mov_b32_e32 v2, 0x3100c0
.Lpcw_spin:
	global_load_dword v3, v2, s[30:31] sc1
	s_waitcnt vmcnt(0)
	v_readfirstlane_b32 s99, v3
	s_cmp_ge_u32 s99, 44
	s_cbranch_scc1 .Lpcw_ok
	s_sleep 1
	s_branch .Lpcw_spin

.Lpcw_skip:
	v_lshlrev_b32_e32 v0, 1, v178
	s_add_u32 s22, s30, 0x2b200000
	v_bitop3_b32 v28, v0, v181, v180 bitop3:0x36
	v_mov_b32_e32 v131, 0
	s_mov_b32 s42, s0
	v_lshl_or_b32 v30, v179, 6, v0
	v_lshlrev_b32_e32 v0, 2, v179
	s_addc_u32 s23, s31, 0
	v_mov_b32_e32 v135, v131
	v_mov_b32_e32 v129, v131
	v_mov_b32_e32 v133, v131
	v_or_b32_e32 v29, 0xffff0000, v179
	s_lshl_b32 s26, s42, 8
	s_lshl_b32 s27, s96, 8
	s_mov_b64 s[0:1], 0xb0000
	v_and_b32_e32 v31, 32, v0
	s_add_i32 s34, 0, 0x18000
	s_mov_b64 s[2:3], 0x80
	s_add_i32 s35, 0, 0x1c000
	s_mov_b64 s[4:5], 0x100
	s_mov_b64 s[8:9], 0x180
	s_mov_b64 s[10:11], 0x80000
	s_mov_b32 s36, 0x80000
	s_mov_b64 s[12:13], 0x90000
	s_mov_b32 s37, 0x90000
	s_mov_b64 s[14:15], 0xa0000
	s_mov_b32 s39, 0xa0000
	s_add_i32 s40, 0, 0x10000
	s_add_i32 s41, 0, 0x14000
	s_branch .LBB0_1105
